# two redundant workgroup barriers removed (after the quarter attention unit for workgroups without deferred work; the in-proj GEMM phase's closing barrier, merged into group_arrive's)
# speedup vs baseline: 1.0094x; 1.0094x over previous
; #define PG8_WAIT_V(n) asm volatile("s_waitcnt vmcnt(" #n ")" ::: "memory")
; #define PG8_BAR __builtin_amdgcn_s_barrier()
; __device__ __forceinline__ void xcd_barrier(const XcdBarrier& b) {
;     asm volatile("s_waitcnt vmcnt(0)" ::: "memory");
;     __syncthreads();
;     if (threadIdx.x == 0) {
;         unsigned* bar = b.bar;
;         __builtin_amdgcn_s_waitcnt(0);
;         unsigned nloc = b.st[0], nx = b.st[1];
;         if (nloc == 0u) { xcd_barrier_complete(bar, b.x, nloc, nx); b.st[0] = nloc; b.st[1] = nx; }
; template <class Epi, class Sched, bool ALIGN_EPI = false, bool SP2 = false>
; __device__ __forceinline__ void gemm_phase(PG8_LAS unsigned char* lds, const Gemm g, const Sched& S, const Epi& E) {
;     ...
;     PG8_WAIT_V(0);
;     if constexpr (!ALIGN_EPI) { if (wr == 0) PG8_BAR; }
;     PG8_BAR;
.LBB0_171:
	s_waitcnt vmcnt(0)
.LBB0_172:
	s_add_u32 s0, s96, 0x900000
	s_addc_u32 s1, s97, 0
	v_writelane_b32 v253, s0, 46
	v_lshrrev_b32_e32 v103, 2, v230
	v_and_b32_e32 v102, 48, v172
	v_writelane_b32 v253, s1, 47
	s_add_u32 s0, s96, 0x200000
	s_addc_u32 s1, s97, 0
	v_writelane_b32 v253, s0, 48
	s_nop 1
	v_writelane_b32 v253, s1, 49
	s_mov_b64 s[0:1], -1
	v_readlane_b32 s2, v253, 31
	v_readlane_b32 s3, v253, 32
	s_and_b64 vcc, exec, s[2:3]
	s_cbranch_vccz .LBB0_253
	s_waitcnt vmcnt(0)
	s_waitcnt vmcnt(0)
	s_barrier
	s_mov_b64 s[0:1], exec
	v_readlane_b32 s2, v253, 23
	v_readlane_b32 s3, v253, 24
	s_and_b64 s[2:3], s[0:1], s[2:3]
	s_mov_b64 exec, s[2:3]
	s_cbranch_execz .LBB0_225
	s_add_i32 s2, 0, 0x20420
	v_mov_b32_e32 v0, s2
	s_waitcnt vmcnt(0) expcnt(0) lgkmcnt(0)
	ds_read_b32 v2, v0
	s_add_i32 s2, 0, 0x20424
	v_mov_b32_e32 v0, s2
	ds_read_b32 v0, v0
	s_waitcnt lgkmcnt(1)
	v_cmp_ne_u32_e32 vcc, 0, v2
	s_cbranch_vccnz .LBB0_189
	v_readlane_b32 s2, v253, 34
	v_readlane_b32 s3, v253, 35
	s_load_dwordx2 s[6:7], s[2:3], 0x4
	s_add_u32 s2, s96, 0x180200
	s_addc_u32 s3, s97, 0
	s_add_u32 s4, s96, 0x180400
	s_addc_u32 s5, s97, 0
	s_waitcnt lgkmcnt(0)
	s_mul_i32 s44, s6, s99
	s_add_u32 s6, s96, 0x180500
	s_mul_i32 s44, s44, s7
	s_addc_u32 s7, s97, 0
	s_add_u32 s8, s96, 0x180600
	s_addc_u32 s9, s97, 0
	s_add_u32 s10, s96, 0x180700
	s_addc_u32 s11, s97, 0
	s_add_u32 s12, s96, 0x180800
	s_addc_u32 s13, s97, 0
	s_add_u32 s14, s96, 0x180900
	s_addc_u32 s15, s97, 0
	s_add_u32 s16, s96, 0x180a00
	s_addc_u32 s17, s97, 0
	s_add_u32 s18, s96, 0x180b00
	s_addc_u32 s19, s97, 0
	s_add_u32 s20, s96, 0x180c00
	s_addc_u32 s21, s97, 0
	s_add_u32 s22, s96, 0x180d00
	s_addc_u32 s23, s97, 0
	s_add_u32 s24, s96, 0x180e00
	s_addc_u32 s25, s97, 0
	s_add_u32 s26, s96, 0x180f00
	s_addc_u32 s27, s97, 0
	s_add_u32 s28, s96, 0x181000
	s_addc_u32 s29, s97, 0
	s_add_u32 s30, s96, 0x181100
	s_addc_u32 s31, s97, 0
	s_add_u32 s34, s96, 0x181200
	s_addc_u32 s35, s97, 0
	s_add_u32 s36, s96, 0x181300
	s_addc_u32 s37, s97, 0
	s_mov_b32 s45, 1
	v_mov_b32_e32 v16, 0
	s_branch .LBB0_177

; __device__ __forceinline__ unsigned xb_ld(unsigned* p)              { return __hip_atomic_load(p, __ATOMIC_RELAXED, __HIP_MEMORY_SCOPE_AGENT); }
; __device__ __forceinline__ void group_wait(unsigned* cnt, unsigned want, unsigned* bar) {
;     if (threadIdx.x == 0) {
;         unsigned sp = 0;
;         while (__hip_atomic_load(cnt, __ATOMIC_RELAXED, __HIP_MEMORY_SCOPE_AGENT) < want) {
;             __builtin_amdgcn_s_sleep(2);
;             if ((++sp & 255u) == 0u) { if (xb_ld(&bar[XB_TMO])) break; if (sp > XB_SPIN_CAP) { atomicAdd(&bar[XB_TMO], 1u); break; } }
;         }
;         __builtin_amdgcn_fence(__ATOMIC_ACQUIRE, "agent");
;         asm volatile("s_waitcnt vmcnt(0)" ::: "memory");
;     }
;     __syncthreads();
; }
; __global__ void __launch_bounds__(NWAVES * 64, 2) fwd_megakernel(Args a) {
;     ...
;             if (l >= 24) {
;                 group_wait(gcc, 32u, (unsigned*)(ws + WS_BAR));
.LBB0_313:
	s_or_b64 exec, exec, s[0:1]
	s_cmpk_lt_u32 s98, 0xc0
	s_cbranch_scc1 .LBB0_339
	s_barrier
	s_mov_b64 s[0:1], exec
	v_readlane_b32 s2, v253, 23
	v_readlane_b32 s3, v253, 24
	s_and_b64 s[2:3], s[0:1], s[2:3]
	s_mov_b64 exec, s[2:3]
	s_cbranch_execz .LBB0_329
	v_mov_b32_e32 v0, 0x20448
	ds_read_b32 v1, v0
	s_waitcnt lgkmcnt(0)
	v_cmp_ne_u32_e32 vcc, 0, v1
	s_cbranch_vccnz .LBB0_329
	v_mov_b32_e32 v0, 0
	buffer_inv sc1
	global_load_dword v1, v0, s[8:9] sc1
	s_waitcnt vmcnt(0)
	v_cmp_lt_u32_e32 vcc, 31, v1
	s_cbranch_vccnz .LBB0_328
	s_add_u32 s2, s96, 0x180200
	s_addc_u32 s3, s97, 0
	s_mov_b32 s12, 1
	s_branch .LBB0_318
